# combo1 + NSA part-A: K (pass 1) and K/V (pass 2) tiles prefetched one iteration ahead
# baseline (speedup 1.0000x reference)
.LBB0_250:
	s_add_i32 s18, s16, s12
	s_lshl_b32 s6, s18, 7
	v_lshl_add_u64 v[0:1], v[92:93], 0, s[6:7]
	flat_load_dwordx4 v[48:51], v[0:1] offset:1024
	flat_load_dwordx4 v[52:55], v[0:1] offset:1056
	flat_load_dwordx4 v[56:59], v[0:1] offset:1088
	flat_load_dwordx4 v[60:63], v[0:1] offset:1120
	s_lshl_b32 s17, s18, 6
	v_mov_b32_e32 v18, 0
	v_mov_b32_e32 v0, 0xff800000
	v_mov_b64_e32 v[16:17], v[90:91]
	v_mov_b32_e32 v19, v106
	s_mov_b32 s6, 0
	s_nop 1
	global_load_dwordx4 v[130:133], v[16:17], off
	global_load_dwordx4 v[134:137], v[16:17], off offset:32
	global_load_dwordx4 v[138:141], v[16:17], off offset:64
	global_load_dwordx4 v[142:145], v[16:17], off offset:96
.LBB0_251:
	v_mov_b32_e32 v20, v0
	v_add_u32_e32 v21, 0xfffffe50, v19
	v_cmp_le_u32_e64 s[44:45], v21, v108
	v_lshl_add_u64 v[16:17], v[16:17], 0, s[24:25]
	s_waitcnt vmcnt(0) lgkmcnt(0)
	v_mfma_f32_32x32x16_bf16 v[0:15], v[130:133], v[48:51], 0
	v_mfma_f32_32x32x16_bf16 v[0:15], v[134:137], v[52:55], v[0:15]
	v_add_u32_e32 v22, s6, v103
	v_cmp_gt_u32_e32 vcc, s75, v22
	s_and_b64 vcc, vcc, s[44:45]
	v_add_u32_e32 v23, 1, v22
	s_add_i32 s6, s6, 32
	v_mfma_f32_32x32x16_bf16 v[0:15], v[138:141], v[56:59], v[0:15]
	v_mfma_f32_32x32x16_bf16 v[0:15], v[142:145], v[60:63], v[0:15]
	s_nop 3
	global_load_dwordx4 v[130:133], v[16:17], off
	global_load_dwordx4 v[134:137], v[16:17], off offset:32
	global_load_dwordx4 v[138:141], v[16:17], off offset:64
	global_load_dwordx4 v[142:145], v[16:17], off offset:96
	s_nop 11
	v_mul_f32_e32 v0, 0x3e38aa3b, v0
	v_cndmask_b32_e32 v21, v212, v0, vcc
	v_cmp_gt_u32_e32 vcc, s75, v23
	v_add_u32_e32 v23, 0xfffffe60, v19
	v_cmp_le_u32_e64 s[44:45], v23, v108
	s_and_b64 vcc, vcc, s[44:45]
	v_mul_f32_e32 v1, 0x3e38aa3b, v1
	v_add_u32_e32 v23, 2, v22
	v_cndmask_b32_e32 v1, v212, v1, vcc
	v_cmp_gt_u32_e32 vcc, s75, v23
	v_add_u32_e32 v23, 0xfffffe70, v19
	v_cmp_le_u32_e64 s[44:45], v23, v108
	s_and_b64 vcc, vcc, s[44:45]
	v_mul_f32_e32 v2, 0x3e38aa3b, v2
	v_add_u32_e32 v23, 3, v22
	v_cndmask_b32_e32 v2, v212, v2, vcc
	v_cmp_gt_u32_e32 vcc, s75, v23
	v_add_u32_e32 v23, 0xfffffe80, v19
	v_cmp_le_u32_e64 s[44:45], v23, v108
	s_and_b64 vcc, vcc, s[44:45]
	v_mul_f32_e32 v3, 0x3e38aa3b, v3
	v_add_u32_e32 v23, 8, v22
	v_cndmask_b32_e32 v3, v212, v3, vcc
	v_cmp_gt_u32_e32 vcc, s75, v23
	v_add_u32_e32 v23, 0xfffffed0, v19
	v_cmp_le_u32_e64 s[44:45], v23, v108
	s_and_b64 vcc, vcc, s[44:45]
	v_mul_f32_e32 v4, 0x3e38aa3b, v4
	v_add_u32_e32 v23, 9, v22
	v_cndmask_b32_e32 v4, v212, v4, vcc
	v_cmp_gt_u32_e32 vcc, s75, v23
	v_add_u32_e32 v23, 0xfffffee0, v19
	v_cmp_le_u32_e64 s[44:45], v23, v108
	s_and_b64 vcc, vcc, s[44:45]
	v_mul_f32_e32 v5, 0x3e38aa3b, v5
	v_add_u32_e32 v23, 10, v22
	v_cndmask_b32_e32 v5, v212, v5, vcc
	v_cmp_gt_u32_e32 vcc, s75, v23
	v_add_u32_e32 v23, 0xfffffef0, v19
	v_cmp_le_u32_e64 s[44:45], v23, v108
	s_and_b64 vcc, vcc, s[44:45]
	v_mul_f32_e32 v6, 0x3e38aa3b, v6
	v_add_u32_e32 v23, 11, v22
	v_cndmask_b32_e32 v6, v212, v6, vcc
	v_cmp_gt_u32_e32 vcc, s75, v23
	v_add_u32_e32 v23, 0xffffff00, v19
	v_cmp_le_u32_e64 s[44:45], v23, v108
	s_and_b64 vcc, vcc, s[44:45]
	v_mul_f32_e32 v7, 0x3e38aa3b, v7
	v_add_u32_e32 v23, 16, v22
	v_cndmask_b32_e32 v7, v212, v7, vcc
	v_cmp_gt_u32_e32 vcc, s75, v23
	v_add_u32_e32 v23, 0xffffff50, v19
	v_cmp_le_u32_e64 s[44:45], v23, v108
	s_and_b64 vcc, vcc, s[44:45]
	v_mul_f32_e32 v8, 0x3e38aa3b, v8
	v_add_u32_e32 v23, 17, v22
	v_cndmask_b32_e32 v8, v212, v8, vcc
	v_cmp_gt_u32_e32 vcc, s75, v23
	v_add_u32_e32 v23, 0xffffff60, v19
	v_cmp_le_u32_e64 s[44:45], v23, v108
	s_and_b64 vcc, vcc, s[44:45]
	v_mul_f32_e32 v9, 0x3e38aa3b, v9
	v_add_u32_e32 v23, 18, v22
	v_cndmask_b32_e32 v9, v212, v9, vcc
	v_cmp_gt_u32_e32 vcc, s75, v23
	v_add_u32_e32 v23, 0xffffff70, v19
	v_cmp_le_u32_e64 s[44:45], v23, v108
	s_and_b64 vcc, vcc, s[44:45]
	v_mul_f32_e32 v10, 0x3e38aa3b, v10
	v_add_u32_e32 v23, 19, v22
	v_cndmask_b32_e32 v10, v212, v10, vcc
	v_cmp_gt_u32_e32 vcc, s75, v23
	v_add_u32_e32 v23, 0xffffff80, v19
	v_cmp_le_u32_e64 s[44:45], v23, v108
	s_and_b64 vcc, vcc, s[44:45]
	v_mul_f32_e32 v11, 0x3e38aa3b, v11
	v_add_u32_e32 v23, 24, v22
	v_cndmask_b32_e32 v11, v212, v11, vcc
	v_cmp_gt_u32_e32 vcc, s75, v23
	v_subrev_u32_e32 v23, 48, v19
	v_cmp_le_u32_e64 s[44:45], v23, v108
	s_and_b64 vcc, vcc, s[44:45]
	v_mul_f32_e32 v12, 0x3e38aa3b, v12
	v_add_u32_e32 v23, 25, v22
	v_cndmask_b32_e32 v12, v212, v12, vcc
	v_cmp_gt_u32_e32 vcc, s75, v23
	v_subrev_u32_e32 v23, 32, v19
	v_max_f32_e32 v0, 0xff800000, v21
	v_cmp_le_u32_e64 s[44:45], v23, v108
	v_max3_f32 v0, v0, v1, v2
	s_and_b64 vcc, vcc, s[44:45]
	v_mul_f32_e32 v13, 0x3e38aa3b, v13
	v_add_u32_e32 v23, 26, v22
	v_max3_f32 v0, v0, v3, v4
	v_cndmask_b32_e32 v13, v212, v13, vcc
	v_cmp_gt_u32_e32 vcc, s75, v23
	v_add_u32_e32 v23, -16, v19
	v_max3_f32 v0, v0, v5, v6
	v_cmp_le_u32_e64 s[44:45], v23, v108
	v_max3_f32 v0, v0, v7, v8
	s_and_b64 vcc, vcc, s[44:45]
	v_mul_f32_e32 v14, 0x3e38aa3b, v14
	v_add_u32_e32 v22, 27, v22
	v_max3_f32 v0, v0, v9, v10
	v_cndmask_b32_e32 v14, v212, v14, vcc
	v_cmp_gt_u32_e32 vcc, s75, v22
	v_cmp_le_u32_e64 s[44:45], v19, v108
	v_max3_f32 v0, v0, v11, v12
	s_and_b64 vcc, vcc, s[44:45]
	v_mul_f32_e32 v15, 0x3e38aa3b, v15
	v_max3_f32 v0, v0, v13, v14
	v_cndmask_b32_e32 v15, v212, v15, vcc
	v_max3_f32 v0, v20, v0, v15
	v_cmp_neq_f32_e32 vcc, s29, v0
	v_add_u32_e32 v19, 0x200, v19
	s_cmp_eq_u32 s15, s6
	v_cndmask_b32_e32 v22, 0, v0, vcc
	v_sub_f32_e32 v21, v21, v22
	v_exp_f32_e32 v21, v21
	v_sub_f32_e32 v1, v1, v22
	v_exp_f32_e32 v1, v1
	v_sub_f32_e32 v2, v2, v22
	v_exp_f32_e32 v2, v2
	v_add_f32_e32 v21, 0, v21
	v_add_f32_e32 v1, v1, v21
	v_add_f32_e32 v1, v2, v1
	v_sub_f32_e32 v2, v3, v22
	v_exp_f32_e32 v2, v2
	v_mov_b32_e32 v3, v18
	v_add_f32_e32 v1, v2, v1
	v_sub_f32_e32 v2, v4, v22
	v_exp_f32_e32 v2, v2
	s_nop 0
	v_add_f32_e32 v1, v2, v1
	v_sub_f32_e32 v2, v5, v22
	v_exp_f32_e32 v2, v2
	s_nop 0
	v_add_f32_e32 v1, v2, v1
	v_sub_f32_e32 v2, v6, v22
	v_exp_f32_e32 v2, v2
	s_nop 0
	v_add_f32_e32 v1, v2, v1
	v_sub_f32_e32 v2, v7, v22
	v_exp_f32_e32 v2, v2
	s_nop 0
	v_add_f32_e32 v1, v2, v1
	v_sub_f32_e32 v2, v8, v22
	v_exp_f32_e32 v2, v2
	s_nop 0
	v_add_f32_e32 v1, v2, v1
	v_sub_f32_e32 v2, v9, v22
	v_exp_f32_e32 v2, v2
	s_nop 0
	v_add_f32_e32 v1, v2, v1
	v_sub_f32_e32 v2, v10, v22
	v_exp_f32_e32 v2, v2
	s_nop 0
	v_add_f32_e32 v1, v2, v1
	v_sub_f32_e32 v2, v11, v22
	v_exp_f32_e32 v2, v2
	s_nop 0
	v_add_f32_e32 v1, v2, v1
	v_sub_f32_e32 v2, v12, v22
	v_exp_f32_e32 v2, v2
	s_nop 0
	v_add_f32_e32 v1, v2, v1
	v_sub_f32_e32 v2, v13, v22
	v_exp_f32_e32 v2, v2
	s_nop 0
	v_add_f32_e32 v1, v2, v1
	v_sub_f32_e32 v2, v14, v22
	v_exp_f32_e32 v2, v2
	s_nop 0
	v_add_f32_e32 v1, v2, v1
	v_sub_f32_e32 v2, v15, v22
	v_exp_f32_e32 v2, v2
	s_nop 0
	v_add_f32_e32 v1, v2, v1
	v_sub_f32_e32 v2, v20, v22
	v_exp_f32_e32 v2, v2
	v_mov_b32_e32 v18, v1
	v_fmac_f32_e32 v18, v3, v2
	s_cbranch_scc0 .LBB0_251
	ds_bpermute_b32 v1, v105, v0
	v_max_f32_e32 v3, v0, v0
	ds_bpermute_b32 v2, v105, v18
	s_waitcnt lgkmcnt(1)
	v_max_f32_e32 v4, v1, v1
	v_max_f32_e32 v3, v3, v4
	v_cmp_neq_f32_e32 vcc, s29, v3
	s_nop 1
	v_cndmask_b32_e32 v89, 0, v3, vcc
	v_sub_f32_e32 v1, v1, v89
	v_sub_f32_e32 v0, v0, v89
	v_exp_f32_e32 v1, v1
	v_exp_f32_e32 v3, v0
	v_mov_b32_e32 v0, 0
	s_waitcnt lgkmcnt(0)
	v_mul_f32_e32 v1, v1, v2
	v_fmac_f32_e32 v1, v18, v3
	v_max_f32_e32 v1, 0xda24260, v1
	v_div_scale_f32 v2, s[20:21], v1, v1, 1.0
	v_rcp_f32_e32 v3, v2
	v_div_scale_f32 v4, vcc, 1.0, v1, 1.0
	s_mov_b32 s6, 0
	v_fma_f32 v5, -v2, v3, 1.0
	v_fmac_f32_e32 v3, v5, v3
	v_mul_f32_e32 v5, v4, v3
	v_fma_f32 v6, -v2, v5, v4
	v_fmac_f32_e32 v5, v6, v3
	v_fma_f32 v2, -v2, v5, v4
	v_div_fmas_f32 v2, v2, v3, v5
	v_div_fixup_f32 v109, v2, v1, 1.0
	v_mov_b64_e32 v[98:99], v[86:87]
	v_mov_b64_e32 v[100:101], v[84:85]
	v_mov_b32_e32 v110, v106
	v_mov_b32_e32 v1, v0
	v_mov_b32_e32 v2, v0
	v_mov_b32_e32 v3, v0
	v_mov_b32_e32 v4, v0
	v_mov_b32_e32 v5, v0
	v_mov_b32_e32 v6, v0
	v_mov_b32_e32 v7, v0
	v_mov_b32_e32 v8, v0
	v_mov_b32_e32 v9, v0
	v_mov_b32_e32 v10, v0
	v_mov_b32_e32 v11, v0
	v_mov_b32_e32 v12, v0
	v_mov_b32_e32 v13, v0
	v_mov_b32_e32 v14, v0
	v_mov_b32_e32 v15, v0
	v_mov_b32_e32 v16, v0
	v_mov_b32_e32 v17, v0
	v_mov_b32_e32 v18, v0
	v_mov_b32_e32 v19, v0
	v_mov_b32_e32 v20, v0
	v_mov_b32_e32 v21, v0
	v_mov_b32_e32 v22, v0
	v_mov_b32_e32 v23, v0
	v_mov_b32_e32 v24, v0
	v_mov_b32_e32 v25, v0
	v_mov_b32_e32 v26, v0
	v_mov_b32_e32 v27, v0
	v_mov_b32_e32 v28, v0
	v_mov_b32_e32 v29, v0
	v_mov_b32_e32 v30, v0
	v_mov_b32_e32 v31, v0
	v_lshl_add_u64 v[32:33], v[100:101], 0, s[8:9]
	s_mov_b32 s19, 0x1e800000
	v_add_co_u32_e32 v36, vcc, s19, v32
	s_mov_b32 s19, 0x1e840000
	s_nop 0
	v_addc_co_u32_e32 v37, vcc, 0, v33, vcc
	s_nop 0
	global_load_dwordx4 v[130:133], v[36:37], off
	global_load_dwordx4 v[134:137], v[36:37], off offset:32
	global_load_dwordx4 v[138:141], v[36:37], off offset:64
	global_load_dwordx4 v[142:145], v[36:37], off offset:96
	v_lshl_add_u64 v[36:37], v[98:99], 0, s[8:9]
	v_add_co_u32_e32 v38, vcc, s19, v36
	s_mov_b32 s19, 0x1e842000
	s_nop 0
	v_addc_co_u32_e32 v39, vcc, 0, v37, vcc
	v_add_co_u32_e32 v36, vcc, s19, v36
	s_nop 1
	v_addc_co_u32_e32 v37, vcc, 0, v37, vcc
	s_nop 0
	global_load_dwordx2 v[146:147], v[38:39], off
	global_load_dwordx2 v[148:149], v[38:39], off offset:16
	global_load_dwordx2 v[150:151], v[38:39], off offset:32
	global_load_dwordx2 v[152:153], v[38:39], off offset:48
	global_load_dwordx2 v[154:155], v[36:37], off
	global_load_dwordx2 v[156:157], v[36:37], off offset:16
	global_load_dwordx2 v[158:159], v[36:37], off offset:32
	global_load_dwordx2 v[160:161], v[36:37], off offset:48
.LBB0_253:
	v_lshl_add_u64 v[32:33], v[100:101], 0, s[8:9]
	s_mov_b32 s19, 0x1e800000
	v_add_co_u32_e32 v36, vcc, s19, v32
	s_mov_b32 s19, 0x1e840000
	s_nop 0
	v_addc_co_u32_e32 v37, vcc, 0, v33, vcc
	s_nop 0
	v_lshl_add_u64 v[162:163], v[36:37], 0, s[24:25]
	v_lshl_add_u64 v[36:37], v[98:99], 0, s[8:9]
	v_add_co_u32_e32 v38, vcc, s19, v36
	s_mov_b32 s19, 0x1e842000
	s_nop 0
	v_addc_co_u32_e32 v39, vcc, 0, v37, vcc
	v_add_co_u32_e32 v36, vcc, s19, v36
	s_nop 1
	v_addc_co_u32_e32 v37, vcc, 0, v37, vcc
	v_add_u32_e32 v111, s6, v103
	s_waitcnt vmcnt(0) lgkmcnt(0)
	v_mov_b64_e32 v[76:77], v[146:147]
	v_mov_b64_e32 v[78:79], v[148:149]
	v_mov_b64_e32 v[72:73], v[150:151]
	v_mov_b64_e32 v[74:75], v[152:153]
	v_mov_b64_e32 v[68:69], v[154:155]
	v_mov_b64_e32 v[70:71], v[156:157]
	v_mov_b64_e32 v[64:65], v[158:159]
	v_mov_b64_e32 v[66:67], v[160:161]
	global_load_dwordx2 v[146:147], v[38:39], off offset:64
	global_load_dwordx2 v[148:149], v[38:39], off offset:80
	global_load_dwordx2 v[150:151], v[38:39], off offset:96
	global_load_dwordx2 v[152:153], v[38:39], off offset:112
	global_load_dwordx2 v[154:155], v[36:37], off offset:64
	global_load_dwordx2 v[156:157], v[36:37], off offset:80
	global_load_dwordx2 v[158:159], v[36:37], off offset:96
	global_load_dwordx2 v[160:161], v[36:37], off offset:112
	v_cmp_gt_u32_e32 vcc, s75, v111
	v_mfma_f32_32x32x16_bf16 v[32:47], v[130:133], v[48:51], 0
	v_mfma_f32_32x32x16_bf16 v[32:47], v[134:137], v[52:55], v[32:47]
	v_add_u32_e32 v112, 0xfffffe50, v110
	v_cmp_le_u32_e64 s[44:45], v112, v108
	s_and_b64 vcc, vcc, s[44:45]
	v_add_u32_e32 v112, 1, v111
	v_mfma_f32_32x32x16_bf16 v[32:47], v[138:141], v[56:59], v[32:47]
	v_mfma_f32_32x32x16_bf16 v[32:47], v[142:145], v[60:63], v[32:47]
	s_nop 3
	global_load_dwordx4 v[130:133], v[162:163], off
	global_load_dwordx4 v[134:137], v[162:163], off offset:32
	global_load_dwordx4 v[138:141], v[162:163], off offset:64
	global_load_dwordx4 v[142:145], v[162:163], off offset:96
	s_nop 11
	v_fma_f32 v32, v32, s28, -v89
	v_exp_f32_e32 v32, v32
	v_fma_f32 v33, v33, s28, -v89
	v_exp_f32_e32 v33, v33
	v_fma_f32 v34, v34, s28, -v89
	v_mul_f32_e32 v32, v109, v32
	v_cndmask_b32_e32 v32, 0, v32, vcc
	v_cmp_gt_u32_e32 vcc, s75, v112
	v_add_u32_e32 v112, 0xfffffe60, v110
	v_cmp_le_u32_e64 s[44:45], v112, v108
	v_exp_f32_e32 v34, v34
	s_and_b64 vcc, vcc, s[44:45]
	v_mul_f32_e32 v33, v109, v33
	v_add_u32_e32 v112, 2, v111
	v_cndmask_b32_e32 v33, 0, v33, vcc
	v_cmp_gt_u32_e32 vcc, s75, v112
	v_add_u32_e32 v112, 0xfffffe70, v110
	v_fma_f32 v35, v35, s28, -v89
	v_cmp_le_u32_e64 s[44:45], v112, v108
	v_exp_f32_e32 v35, v35
	s_and_b64 vcc, vcc, s[44:45]
	v_mul_f32_e32 v34, v109, v34
	v_add_u32_e32 v112, 3, v111
	v_cndmask_b32_e32 v34, 0, v34, vcc
	v_cmp_gt_u32_e32 vcc, s75, v112
	v_add_u32_e32 v112, 0xfffffe80, v110
	v_fma_f32 v36, v36, s28, -v89
	v_cmp_le_u32_e64 s[44:45], v112, v108
	v_exp_f32_e32 v36, v36
	s_and_b64 vcc, vcc, s[44:45]
	v_mul_f32_e32 v35, v109, v35
	v_add_u32_e32 v112, 8, v111
	v_cndmask_b32_e32 v35, 0, v35, vcc
	v_cmp_gt_u32_e32 vcc, s75, v112
	v_add_u32_e32 v112, 0xfffffed0, v110
	v_fma_f32 v37, v37, s28, -v89
	v_cmp_le_u32_e64 s[44:45], v112, v108
	v_exp_f32_e32 v37, v37
	s_and_b64 vcc, vcc, s[44:45]
	v_mul_f32_e32 v36, v109, v36
	v_add_u32_e32 v112, 9, v111
	v_cndmask_b32_e32 v36, 0, v36, vcc
	v_cmp_gt_u32_e32 vcc, s75, v112
	v_add_u32_e32 v112, 0xfffffee0, v110
	v_fma_f32 v38, v38, s28, -v89
	v_cmp_le_u32_e64 s[44:45], v112, v108
	v_exp_f32_e32 v38, v38
	s_and_b64 vcc, vcc, s[44:45]
	v_mul_f32_e32 v37, v109, v37
	v_add_u32_e32 v112, 10, v111
	v_cndmask_b32_e32 v37, 0, v37, vcc
	v_cmp_gt_u32_e32 vcc, s75, v112
	v_add_u32_e32 v112, 0xfffffef0, v110
	v_fma_f32 v39, v39, s28, -v89
	v_cmp_le_u32_e64 s[44:45], v112, v108
	v_exp_f32_e32 v39, v39
	s_and_b64 vcc, vcc, s[44:45]
	v_mul_f32_e32 v38, v109, v38
	v_add_u32_e32 v112, 11, v111
	v_cndmask_b32_e32 v38, 0, v38, vcc
	v_cmp_gt_u32_e32 vcc, s75, v112
	v_add_u32_e32 v112, 0xffffff00, v110
	v_fma_f32 v40, v40, s28, -v89
	v_cmp_le_u32_e64 s[44:45], v112, v108
	v_exp_f32_e32 v40, v40
	s_and_b64 vcc, vcc, s[44:45]
	v_mul_f32_e32 v39, v109, v39
	v_add_u32_e32 v112, 16, v111
	v_cndmask_b32_e32 v39, 0, v39, vcc
	v_cmp_gt_u32_e32 vcc, s75, v112
	v_add_u32_e32 v112, 0xffffff50, v110
	v_fma_f32 v41, v41, s28, -v89
	v_cmp_le_u32_e64 s[44:45], v112, v108
	v_exp_f32_e32 v41, v41
	s_and_b64 vcc, vcc, s[44:45]
	v_mul_f32_e32 v40, v109, v40
	v_add_u32_e32 v112, 17, v111
	v_cndmask_b32_e32 v40, 0, v40, vcc
	v_cmp_gt_u32_e32 vcc, s75, v112
	v_add_u32_e32 v112, 0xffffff60, v110
	v_fma_f32 v42, v42, s28, -v89
	v_cmp_le_u32_e64 s[44:45], v112, v108
	v_exp_f32_e32 v42, v42
	s_and_b64 vcc, vcc, s[44:45]
	v_mul_f32_e32 v41, v109, v41
	v_add_u32_e32 v112, 18, v111
	v_cndmask_b32_e32 v41, 0, v41, vcc
	v_cmp_gt_u32_e32 vcc, s75, v112
	v_add_u32_e32 v112, 0xffffff70, v110
	v_cmp_le_u32_e64 s[44:45], v112, v108
	s_and_b64 vcc, vcc, s[44:45]
	v_mul_f32_e32 v42, v109, v42
	v_cndmask_b32_e32 v112, 0, v42, vcc
	v_add_u32_e32 v42, 19, v111
	v_cmp_gt_u32_e32 vcc, s75, v42
	v_add_u32_e32 v42, 0xffffff80, v110
	v_cmp_le_u32_e64 s[44:45], v42, v108
	v_fma_f32 v42, v43, s28, -v89
	v_exp_f32_e32 v42, v42
	s_and_b64 vcc, vcc, s[44:45]
	v_fma_f32 v43, 0.5, v35, v34
	v_add_f32_e32 v117, v36, v37
	v_mul_f32_e32 v42, v109, v42
	v_cndmask_b32_e32 v113, 0, v42, vcc
	v_add_u32_e32 v42, 24, v111
	v_cmp_gt_u32_e32 vcc, s75, v42
	v_subrev_u32_e32 v42, 48, v110
	v_cmp_le_u32_e64 s[44:45], v42, v108
	v_fma_f32 v42, v44, s28, -v89
	v_exp_f32_e32 v42, v42
	s_and_b64 vcc, vcc, s[44:45]
	v_fma_f32 v118, 0.5, v39, v38
	v_add_f32_e32 v117, v117, v118
	v_mul_f32_e32 v42, v109, v42
	v_cndmask_b32_e32 v114, 0, v42, vcc
	v_add_u32_e32 v42, 25, v111
	v_cmp_gt_u32_e32 vcc, s75, v42
	v_subrev_u32_e32 v42, 32, v110
	v_cmp_le_u32_e64 s[44:45], v42, v108
	v_fma_f32 v42, v45, s28, -v89
	v_exp_f32_e32 v42, v42
	s_and_b64 vcc, vcc, s[44:45]
	v_mul_f32_e32 v42, v109, v42
	v_cndmask_b32_e32 v115, 0, v42, vcc
	v_add_u32_e32 v42, 26, v111
	v_cmp_gt_u32_e32 vcc, s75, v42
	v_add_u32_e32 v42, -16, v110
	v_cmp_le_u32_e64 s[44:45], v42, v108
	v_fma_f32 v42, v46, s28, -v89
	v_exp_f32_e32 v42, v42
	s_and_b64 vcc, vcc, s[44:45]
	v_cmp_le_u32_e64 s[44:45], v110, v108
	v_mul_f32_e32 v42, v109, v42
	v_cndmask_b32_e32 v46, 0, v42, vcc
	v_add_u32_e32 v42, 27, v111
	v_cmp_gt_u32_e32 vcc, s75, v42
	v_fma_f32 v42, v47, s28, -v89
	v_exp_f32_e32 v42, v42
	s_and_b64 vcc, vcc, s[44:45]
	v_add_u32_e32 v111, s6, v107
	v_add_u32_e32 v116, 0x1000, v111
	v_mul_f32_e32 v42, v109, v42
	v_cndmask_b32_e32 v47, 0, v42, vcc
	v_add_f32_e32 v42, v32, v33
	v_add_f32_e32 v44, v42, v43
	ds_read2_b32 v[42:43], v111 offset1:2
	v_cvt_pk_bf16_f32 v32, v32, v33
	v_cvt_pk_bf16_f32 v33, v34, v35
	v_cvt_pk_bf16_f32 v34, v36, v37
	v_cvt_pk_bf16_f32 v36, v40, v41
	s_waitcnt lgkmcnt(0)
	v_add_f32_e32 v42, v42, v44
	ds_read2_b32 v[44:45], v116 offset0:32 offset1:34
	v_add_f32_e32 v43, v43, v117
	ds_write2_b32 v111, v42, v43 offset1:2
	v_add_f32_e32 v42, v40, v41
	v_fma_f32 v43, 0.5, v113, v112
	s_waitcnt lgkmcnt(1)
	v_fma_f32 v44, 0.5, v35, v44
	v_cvt_pk_bf16_f32 v35, v38, v39
	v_fmac_f32_e32 v45, 0.5, v39
	ds_write2_b32 v116, v44, v45 offset0:32 offset1:34
	v_mfma_f32_32x32x16_bf16 v[0:15], v[76:79], v[32:35], v[0:15]
	v_add_f32_e32 v44, v42, v43
	ds_read2_b32 v[42:43], v111 offset0:4 offset1:6
	v_cvt_pk_bf16_f32 v37, v112, v113
	v_cvt_pk_bf16_f32 v38, v114, v115
	v_cvt_pk_bf16_f32 v39, v46, v47
	v_add_f32_e32 v117, v114, v115
	s_waitcnt lgkmcnt(0)
	v_add_f32_e32 v42, v44, v42
	v_mfma_f32_32x32x16_bf16 v[16:31], v[68:71], v[32:35], v[16:31]
	ds_read2_b32 v[44:45], v116 offset0:36 offset1:38
	v_fma_f32 v118, 0.5, v47, v46
	v_add_f32_e32 v117, v117, v118
	v_add_f32_e32 v43, v117, v43
	ds_write2_b32 v111, v42, v43 offset0:4 offset1:6
	s_waitcnt lgkmcnt(1)
	v_fma_f32 v44, 0.5, v113, v44
	v_fmac_f32_e32 v45, 0.5, v47
	v_mfma_f32_32x32x16_bf16 v[0:15], v[72:75], v[36:39], v[0:15]
	ds_write2_b32 v116, v44, v45 offset0:36 offset1:38
	v_mfma_f32_32x32x16_bf16 v[16:31], v[64:67], v[36:39], v[16:31]
	s_add_i32 s6, s6, 32
	v_add_u32_e32 v110, 0x200, v110
	v_lshl_add_u64 v[100:101], v[100:101], 0, s[24:25]
	s_cmp_eq_u32 s15, s6
	v_lshl_add_u64 v[98:99], v[98:99], 0, 64
	s_cbranch_scc0 .LBB0_253
	s_mul_i32 s6, s18, 3
	v_lshl_add_u64 v[32:33], s[6:7], 1, v[94:95]
	flat_load_ushort v32, v[32:33]
	s_lshl_b32 s6, s17, 1
	s_waitcnt vmcnt(0) lgkmcnt(0)
	v_lshlrev_b32_e32 v32, 16, v32
	v_mul_f32_e32 v32, 0xbfb8aa3b, v32
	v_exp_f32_e32 v32, v32
	s_nop 0
	v_add_f32_e32 v32, 1.0, v32
	v_rcp_f32_e32 v32, v32
	s_nop 0
	v_pk_mul_f32 v[0:1], v[0:1], v[32:33] op_sel_hi:[1,0]
	v_pk_mul_f32 v[2:3], v[2:3], v[32:33] op_sel_hi:[1,0]
	v_pk_mul_f32 v[16:17], v[16:17], v[32:33] op_sel_hi:[1,0]
	v_pk_mul_f32 v[18:19], v[18:19], v[32:33] op_sel_hi:[1,0]
	v_pk_mul_f32 v[4:5], v[4:5], v[32:33] op_sel_hi:[1,0]
	v_pk_mul_f32 v[20:21], v[20:21], v[32:33] op_sel_hi:[1,0]
	v_pk_mul_f32 v[6:7], v[6:7], v[32:33] op_sel_hi:[1,0]
	v_pk_mul_f32 v[22:23], v[22:23], v[32:33] op_sel_hi:[1,0]
	v_pk_mul_f32 v[8:9], v[8:9], v[32:33] op_sel_hi:[1,0]
	v_pk_mul_f32 v[24:25], v[24:25], v[32:33] op_sel_hi:[1,0]
	v_pk_mul_f32 v[10:11], v[10:11], v[32:33] op_sel_hi:[1,0]
	v_pk_mul_f32 v[26:27], v[26:27], v[32:33] op_sel_hi:[1,0]
	v_pk_mul_f32 v[12:13], v[12:13], v[32:33] op_sel_hi:[1,0]
	v_pk_mul_f32 v[28:29], v[28:29], v[32:33] op_sel_hi:[1,0]
	v_pk_mul_f32 v[14:15], v[14:15], v[32:33] op_sel_hi:[1,0]
	v_pk_mul_f32 v[30:31], v[30:31], v[32:33] op_sel_hi:[1,0]
	v_lshl_add_u64 v[32:33], v[96:97], 0, s[6:7]
	v_cvt_pk_bf16_f32 v0, v0, v1
	v_cvt_pk_bf16_f32 v1, v2, v3
	flat_store_dwordx2 v[32:33], v[0:1]
	v_cvt_pk_bf16_f32 v0, v4, v5
	v_cvt_pk_bf16_f32 v1, v6, v7
	flat_store_dwordx2 v[32:33], v[0:1] offset:16
	v_cvt_pk_bf16_f32 v0, v8, v9
	v_cvt_pk_bf16_f32 v1, v10, v11
	flat_store_dwordx2 v[32:33], v[0:1] offset:32
	v_cvt_pk_bf16_f32 v0, v12, v13
	v_cvt_pk_bf16_f32 v1, v14, v15
	flat_store_dwordx2 v[32:33], v[0:1] offset:48
	v_cvt_pk_bf16_f32 v0, v16, v17
	v_cvt_pk_bf16_f32 v1, v18, v19
	flat_store_dwordx2 v[32:33], v[0:1] offset:64
	v_cvt_pk_bf16_f32 v0, v20, v21
	v_cvt_pk_bf16_f32 v1, v22, v23
	flat_store_dwordx2 v[32:33], v[0:1] offset:80
	v_cvt_pk_bf16_f32 v0, v24, v25
	v_cvt_pk_bf16_f32 v1, v26, v27
	flat_store_dwordx2 v[32:33], v[0:1] offset:96
	v_cvt_pk_bf16_f32 v0, v28, v29
	v_cvt_pk_bf16_f32 v1, v30, v31
	flat_store_dwordx2 v[32:33], v[0:1] offset:112
	s_add_i32 s16, s16, 1
	s_cmp_eq_u32 s16, 4
	s_cbranch_scc0 .LBB0_250
	v_add_u32_e32 v0, 0x1080, v102
	ds_read2_b32 v[0:1], v0 offset1:1
	v_add_u32_e32 v10, 0x1088, v102
	v_add_u32_e32 v12, 0x1090, v102
	ds_read2_b32 v[2:3], v102 offset0:1 offset1:2
	ds_read2_b32 v[4:5], v102 offset0:3 offset1:4
	ds_read2_b32 v[6:7], v102 offset0:5 offset1:6
	ds_read2_b32 v[8:9], v102 offset0:7 offset1:8
	ds_read2_b32 v[10:11], v10 offset1:1
	ds_read2_b32 v[12:13], v12 offset1:1
	ds_read_b32 v28, v102 offset:4344
	s_lshr_b32 s8, s13, 6
	s_waitcnt lgkmcnt(0)
	v_add_f32_e32 v1, v3, v1
	v_add_u32_e32 v3, 0x1098, v102
	v_add_u32_e32 v16, 0x10a0, v102
	v_add_u32_e32 v18, 0x10a8, v102
	v_add_u32_e32 v20, 0x10b0, v102
	s_cmpk_gt_u32 s13, 0x7f
	ds_read2_b32 v[14:15], v3 offset1:1
	ds_read2_b32 v[16:17], v16 offset1:1
	ds_read2_b32 v[18:19], v18 offset1:1
	ds_read2_b32 v[46:47], v20 offset1:1
	ds_read2_b32 v[48:49], v102 offset0:9 offset1:10
	ds_read2_b32 v[50:51], v102 offset0:11 offset1:12
	ds_read2_b32 v[52:53], v102 offset0:13 offset1:14
	ds_read2_b32 v[54:55], v102 offset0:15 offset1:16
	v_add_u32_e32 v3, 0x10b8, v102
	v_add_u32_e32 v20, 0x10c0, v102
	v_add_u32_e32 v21, 0x10c8, v102
	v_add_u32_e32 v22, 0x10d0, v102
	s_cselect_b64 vcc, -1, 0
	s_and_b32 s9, s14, 0x7fffffc
	ds_read2_b32 v[56:57], v3 offset1:1
	ds_read2_b32 v[58:59], v20 offset1:1
	ds_read2_b32 v[60:61], v21 offset1:1
	ds_read2_b32 v[20:21], v22 offset1:1
	ds_read2_b32 v[62:63], v102 offset0:17 offset1:18
	ds_read2_b32 v[64:65], v102 offset0:19 offset1:20
	ds_read2_b32 v[42:43], v102 offset0:21 offset1:22
	ds_read2_b32 v[22:23], v102 offset0:23 offset1:24
	v_add_u32_e32 v3, 0x10d8, v102
	v_add_u32_e32 v24, 0x10e0, v102
	v_add_u32_e32 v26, 0x10e8, v102
	s_cmp_lg_u32 s9, 4
	v_add_u32_e32 v29, 0x10f0, v102
	ds_read2_b32 v[40:41], v3 offset1:1
	ds_read2_b32 v[24:25], v24 offset1:1
	ds_read2_b32 v[26:27], v26 offset1:1
	ds_read2_b32 v[30:31], v29 offset1:1
	ds_read2_b32 v[38:39], v102 offset0:25 offset1:26
	ds_read2_b32 v[36:37], v102 offset0:27 offset1:28
	ds_read2_b32 v[34:35], v102 offset0:29 offset1:30
	ds_read_b32 v32, v102 offset:124
	v_cndmask_b32_e32 v1, v212, v1, vcc
	v_mov_b32_e32 v44, 0x7f800000
	s_cselect_b64 vcc, -1, 0
	v_mov_b32_e32 v66, v4
	v_mov_b32_e32 v67, v2
	v_mov_b32_e32 v2, v10
	v_mov_b32_e32 v3, v0
	s_cmpk_gt_u32 s13, 0xbf
	v_cndmask_b32_e32 v45, v44, v1, vcc
	v_pk_add_f32 v[0:1], v[66:67], v[2:3]
	s_cselect_b64 vcc, -1, 0
	s_cmp_gt_u32 s13, 63
	v_cndmask_b32_e32 v0, v212, v0, vcc
	s_cselect_b64 vcc, -1, 0
	s_add_i32 s6, s8, -3
	s_add_i32 s14, s8, -1
	s_cmp_gt_u32 s14, 1
	v_cndmask_b32_e32 v1, v212, v1, vcc
	s_cselect_b64 vcc, -1, 0
	s_cmp_gt_u32 s6, 1
	v_cndmask_b32_e32 v1, v44, v1, vcc
	s_cselect_b64 vcc, -1, 0
	v_mov_b32_e32 v4, v7
	v_mov_b32_e32 v10, v13
	s_cmpk_gt_u32 s13, 0x17f
	v_cndmask_b32_e32 v0, v44, v0, vcc
	v_pk_add_f32 v[2:3], v[4:5], v[10:11]
	s_cselect_b64 vcc, -1, 0
	s_cmpk_gt_u32 s13, 0xff
	v_cndmask_b32_e32 v2, v212, v2, vcc
	s_cselect_b64 vcc, -1, 0
	s_cmp_lg_u32 s9, 8
	v_cndmask_b32_e32 v3, v212, v3, vcc
	s_cselect_b64 vcc, -1, 0
	s_cmp_lg_u32 s9, 12
	v_cndmask_b32_e32 v3, v44, v3, vcc
	s_cselect_b64 vcc, -1, 0
	v_mov_b32_e32 v4, v8
	v_mov_b32_e32 v5, v6
	s_waitcnt lgkmcnt(0)
	v_mov_b32_e32 v6, v14
	v_mov_b32_e32 v7, v12
	s_cmpk_gt_u32 s13, 0x1bf
	v_cndmask_b32_e32 v2, v44, v2, vcc
	v_pk_add_f32 v[4:5], v[4:5], v[6:7]
	s_cselect_b64 vcc, -1, 0
	s_cmpk_gt_u32 s13, 0x13f
	v_cndmask_b32_e32 v4, v212, v4, vcc
	s_cselect_b64 vcc, -1, 0
	s_add_i32 s14, s8, -7
	s_add_i32 s15, s8, -5
	s_cmp_gt_u32 s15, 1
	v_cndmask_b32_e32 v5, v212, v5, vcc
	s_cselect_b64 vcc, -1, 0
	s_cmp_gt_u32 s14, 1
	v_cndmask_b32_e32 v5, v44, v5, vcc
	s_cselect_b64 vcc, -1, 0
	v_mov_b32_e32 v8, v49
	v_mov_b32_e32 v14, v17
	s_cmpk_gt_u32 s13, 0x27f
	v_cndmask_b32_e32 v4, v44, v4, vcc
	v_pk_add_f32 v[6:7], v[8:9], v[14:15]
	s_cselect_b64 vcc, -1, 0
	s_cmpk_gt_u32 s13, 0x1ff
	v_cndmask_b32_e32 v6, v212, v6, vcc
	s_cselect_b64 vcc, -1, 0
	s_cmp_lg_u32 s9, 16
	v_cndmask_b32_e32 v7, v212, v7, vcc
	s_cselect_b64 vcc, -1, 0
	s_cmp_lg_u32 s9, 20
	v_cndmask_b32_e32 v7, v44, v7, vcc
	s_cselect_b64 vcc, -1, 0
	v_mov_b32_e32 v8, v50
	v_mov_b32_e32 v9, v48
	v_mov_b32_e32 v10, v18
	v_mov_b32_e32 v11, v16
	s_cmpk_gt_u32 s13, 0x2bf
	v_cndmask_b32_e32 v6, v44, v6, vcc
	v_pk_add_f32 v[8:9], v[8:9], v[10:11]
	s_cselect_b64 vcc, -1, 0
	s_cmpk_gt_u32 s13, 0x23f
	v_cndmask_b32_e32 v8, v212, v8, vcc
	s_cselect_b64 vcc, -1, 0
	s_add_i32 s14, s8, -11
	s_add_i32 s15, s8, -9
	s_cmp_gt_u32 s15, 1
	v_cndmask_b32_e32 v9, v212, v9, vcc
	s_cselect_b64 vcc, -1, 0
	s_cmp_gt_u32 s14, 1
	v_cndmask_b32_e32 v9, v44, v9, vcc
	s_cselect_b64 vcc, -1, 0
	v_mov_b32_e32 v50, v53
	v_mov_b32_e32 v18, v47
	s_cmpk_gt_u32 s13, 0x37f
	v_cndmask_b32_e32 v8, v44, v8, vcc
	v_pk_add_f32 v[10:11], v[50:51], v[18:19]
	s_cselect_b64 vcc, -1, 0
	s_cmpk_gt_u32 s13, 0x2ff
	v_cndmask_b32_e32 v10, v212, v10, vcc
	s_cselect_b64 vcc, -1, 0
	s_cmp_lg_u32 s9, 24
	v_cndmask_b32_e32 v11, v212, v11, vcc
	s_cselect_b64 vcc, -1, 0
	s_cmp_lg_u32 s9, 28
	v_cndmask_b32_e32 v11, v44, v11, vcc
	s_cselect_b64 vcc, -1, 0
	v_mov_b32_e32 v12, v54
	v_mov_b32_e32 v13, v52
	v_mov_b32_e32 v14, v56
	v_mov_b32_e32 v15, v46
	s_cmpk_gt_u32 s13, 0x3bf
	v_cndmask_b32_e32 v10, v44, v10, vcc
	v_pk_add_f32 v[12:13], v[12:13], v[14:15]
	s_cselect_b64 vcc, -1, 0
	s_cmpk_gt_u32 s13, 0x33f
	v_cndmask_b32_e32 v12, v212, v12, vcc
	s_cselect_b64 vcc, -1, 0
	s_add_i32 s14, s8, -15
	s_add_i32 s15, s8, -13
	s_cmp_gt_u32 s15, 1
	v_cndmask_b32_e32 v13, v212, v13, vcc
	s_cselect_b64 vcc, -1, 0
	s_cmp_gt_u32 s14, 1
	v_cndmask_b32_e32 v13, v44, v13, vcc
	s_cselect_b64 vcc, -1, 0
	v_mov_b32_e32 v54, v63
	v_mov_b32_e32 v56, v59
	s_cmpk_gt_u32 s13, 0x47f
	v_cndmask_b32_e32 v12, v44, v12, vcc
	v_pk_add_f32 v[14:15], v[54:55], v[56:57]
	s_cselect_b64 vcc, -1, 0
	s_cmpk_gt_u32 s13, 0x3ff
	v_cndmask_b32_e32 v14, v212, v14, vcc
	s_cselect_b64 vcc, -1, 0
	s_cmp_lg_u32 s9, 32
	v_cndmask_b32_e32 v15, v212, v15, vcc
	s_cselect_b64 vcc, -1, 0
	s_cmp_lg_u32 s9, 36
	v_cndmask_b32_e32 v15, v44, v15, vcc
	s_cselect_b64 vcc, -1, 0
	v_mov_b32_e32 v16, v64
	v_mov_b32_e32 v17, v62
	v_mov_b32_e32 v18, v60
	v_mov_b32_e32 v19, v58
	s_cmpk_gt_u32 s13, 0x4bf
	v_cndmask_b32_e32 v14, v44, v14, vcc
	v_pk_add_f32 v[16:17], v[16:17], v[18:19]
	s_cselect_b64 vcc, -1, 0
	s_cmpk_gt_u32 s13, 0x43f
	v_cndmask_b32_e32 v16, v212, v16, vcc
	s_cselect_b64 vcc, -1, 0
	s_sub_i32 s14, s8, 19
	s_sub_i32 s15, s8, 17
	s_cmp_gt_u32 s15, 1
	v_cndmask_b32_e32 v17, v212, v17, vcc
	s_cselect_b64 vcc, -1, 0
	s_cmp_gt_u32 s14, 1
	v_cndmask_b32_e32 v17, v44, v17, vcc
	s_cselect_b64 vcc, -1, 0
	v_mov_b32_e32 v64, v43
	v_mov_b32_e32 v60, v21
	s_cmpk_gt_u32 s13, 0x57f
	v_cndmask_b32_e32 v16, v44, v16, vcc
	v_pk_add_f32 v[18:19], v[64:65], v[60:61]
	s_cselect_b64 vcc, -1, 0
	s_cmpk_gt_u32 s13, 0x4ff
	v_cndmask_b32_e32 v18, v212, v18, vcc
	s_cselect_b64 vcc, -1, 0
	s_cmp_lg_u32 s9, 40
	v_cndmask_b32_e32 v19, v212, v19, vcc
	s_cselect_b64 vcc, -1, 0
	s_cmp_lg_u32 s9, 44
	v_cndmask_b32_e32 v19, v44, v19, vcc
	s_cselect_b64 vcc, -1, 0
	v_mov_b32_e32 v46, v22
	v_mov_b32_e32 v47, v42
	v_mov_b32_e32 v42, v40
	v_mov_b32_e32 v43, v20
	s_cmpk_gt_u32 s13, 0x5bf
	v_cndmask_b32_e32 v18, v44, v18, vcc
	v_pk_add_f32 v[20:21], v[46:47], v[42:43]
	s_cselect_b64 vcc, -1, 0
	s_cmpk_gt_u32 s13, 0x53f
	v_cndmask_b32_e32 v20, v212, v20, vcc
	s_cselect_b64 vcc, -1, 0
	s_sub_i32 s14, s8, 23
	s_sub_i32 s15, s8, 21
	s_cmp_gt_u32 s15, 1
	v_cndmask_b32_e32 v21, v212, v21, vcc
	s_cselect_b64 vcc, -1, 0
	s_cmp_gt_u32 s14, 1
	v_cndmask_b32_e32 v21, v44, v21, vcc
	s_cselect_b64 vcc, -1, 0
	v_mov_b32_e32 v22, v39
	v_mov_b32_e32 v40, v25
	s_cmpk_gt_u32 s13, 0x67f
	v_cndmask_b32_e32 v20, v44, v20, vcc
	v_pk_add_f32 v[22:23], v[22:23], v[40:41]
	s_cselect_b64 vcc, -1, 0
	s_cmpk_gt_u32 s13, 0x5ff
	v_cndmask_b32_e32 v22, v212, v22, vcc
	s_cselect_b64 vcc, -1, 0
	s_cmp_lg_u32 s9, 48
	v_cndmask_b32_e32 v23, v212, v23, vcc
	s_cselect_b64 vcc, -1, 0
	s_cmp_lg_u32 s9, 52
	v_cndmask_b32_e32 v23, v44, v23, vcc
	s_cselect_b64 vcc, -1, 0
	v_mov_b32_e32 v40, v36
	v_mov_b32_e32 v41, v38
	v_mov_b32_e32 v38, v26
	v_mov_b32_e32 v39, v24
	s_cmpk_gt_u32 s13, 0x6bf
	v_cndmask_b32_e32 v22, v44, v22, vcc
	v_pk_add_f32 v[24:25], v[40:41], v[38:39]
	s_cselect_b64 vcc, -1, 0
	s_cmpk_gt_u32 s13, 0x63f
	v_cndmask_b32_e32 v24, v212, v24, vcc
	s_cselect_b64 vcc, -1, 0
	s_sub_i32 s14, s8, 27
	s_sub_i32 s15, s8, 25
	s_cmp_gt_u32 s15, 1
	v_cndmask_b32_e32 v25, v212, v25, vcc
	s_cselect_b64 vcc, -1, 0
	s_cmp_gt_u32 s14, 1
	v_cndmask_b32_e32 v25, v44, v25, vcc
	s_cselect_b64 vcc, -1, 0
	v_mov_b32_e32 v36, v35
	v_mov_b32_e32 v26, v31
	s_cmpk_gt_u32 s13, 0x77f
	v_cndmask_b32_e32 v24, v44, v24, vcc
	v_pk_add_f32 v[26:27], v[36:37], v[26:27]
	s_cselect_b64 vcc, -1, 0
	s_cmpk_gt_u32 s13, 0x6ff
	v_cndmask_b32_e32 v26, v212, v26, vcc
	s_cselect_b64 vcc, -1, 0
	s_cmp_lg_u32 s9, 56
	v_cndmask_b32_e32 v27, v212, v27, vcc
	s_cselect_b64 vcc, -1, 0
	s_cmp_lg_u32 s9, 60
	v_cndmask_b32_e32 v27, v44, v27, vcc
	s_cselect_b64 vcc, -1, 0
	v_mov_b32_e32 v33, v34
	v_mov_b32_e32 v29, v30
	s_cmpk_gt_u32 s13, 0x7bf
	v_cndmask_b32_e32 v26, v44, v26, vcc
	v_pk_add_f32 v[28:29], v[32:33], v[28:29]
	s_cselect_b64 vcc, -1, 0
	s_cmpk_gt_u32 s13, 0x73f
	v_cndmask_b32_e32 v28, v212, v28, vcc
	s_cselect_b64 vcc, -1, 0
	s_sub_i32 s9, s8, 31
	s_sub_i32 s8, s8, 29
	s_cmp_gt_u32 s8, 1
	v_cndmask_b32_e32 v29, v212, v29, vcc
	s_cselect_b64 vcc, -1, 0
	s_cmp_gt_u32 s9, 1
	v_cndmask_b32_e32 v29, v44, v29, vcc
	s_cselect_b64 vcc, -1, 0
	s_mov_b32 s6, 8
	v_cndmask_b32_e32 v28, v44, v28, vcc
	v_mov_b32_e32 v30, 0
